# phase-5 panel meets without the L2 write-back (statistics are device-scope atomics)
# speedup vs baseline: 1.0145x; 1.0145x over previous
.LBB0_1292:
	s_or_b64 exec, exec, s[0:1]
	s_waitcnt vmcnt(0)
	s_waitcnt lgkmcnt(0)
	s_barrier
	s_mov_b64 s[0:1], exec
	v_readlane_b32 s2, v251, 3
	v_readlane_b32 s3, v251, 4
	s_and_b64 s[2:3], s[0:1], s[2:3]
	s_xor_b64 s[0:1], s[2:3], s[0:1]
	s_mov_b64 exec, s[2:3]
	s_cbranch_execz .LBB0_1306
	s_lshl_b32 s2, s34, 6
	s_ashr_i32 s3, s2, 31
	s_lshl_b64 s[2:3], s[2:3], 2
	s_add_u32 s2, s30, s2
	s_addc_u32 s3, s31, s3
	v_mov_b32_e32 v2, 0
	s_waitcnt vmcnt(0)
	s_waitcnt vmcnt(0)
	v_mov_b32_e32 v3, 1
	global_atomic_add v2, v3, s[2:3]
	s_mov_b32 s6, 0x1000000
	s_branch .LBB0_1296

.LBB0_1310:
	s_or_b64 exec, exec, s[0:1]
	s_waitcnt vmcnt(0)
	s_waitcnt lgkmcnt(0)
	s_barrier
	s_mov_b64 s[0:1], exec
	v_readlane_b32 s4, v251, 3
	v_readlane_b32 s5, v251, 4
	s_and_b64 s[4:5], s[0:1], s[4:5]
	s_mov_b64 exec, s[4:5]
	s_cbranch_execz .LBB0_1326
	s_lshl_b32 s2, s2, 2
	s_mov_b64 s[4:5], exec
	s_add_u32 s2, s30, s2
	s_addc_u32 s3, s31, 0
	s_waitcnt vmcnt(0)
	s_waitcnt vmcnt(0)
	v_mbcnt_lo_u32_b32 v3, s4, 0
	s_add_u32 s2, s2, 0x4000
	v_mbcnt_hi_u32_b32 v3, s5, v3
	s_addc_u32 s3, s3, 0
	v_cmp_eq_u32_e32 vcc, 0, v3
	s_and_saveexec_b64 s[6:7], vcc
	s_cbranch_execz .LBB0_1313
	s_bcnt1_i32_b64 s4, s[4:5]
	v_mov_b32_e32 v3, 0
	v_mov_b32_e32 v13, s4
	global_atomic_add v3, v13, s[2:3]
